# PS on top of FN 13,16: layer 1's first norm loads the 11 split-K partial slabs of a context row in two batches (6+5 in flight) instead of 11 dependent round trips; same summation order
# speedup vs baseline: 1.0038x; 1.0038x over previous
; #define GAS __attribute__((address_space(1)))
; __device__ void phase_norm(const Params& p, int l, int which) {
;     ...
;         if (l == 1 && which == 0 && row >= NL) {
;             GAS const f32x4* pp = (GAS const f32x4*)(unsigned long long)((const float*)(p.ws + OFF_PART) + (size_t)(row - NL) * DM);
; #pragma unroll 1
;             for (int ks = 0; ks < SK_S; ++ks) {
;                 f32x4 t[4];
; #pragma unroll
;                 for (int j = 0; j < 4; ++j) t[j] = pp[(size_t)ks * (1024 * DM / 4) + lane + 64 * j];
;                 asm volatile("" ::: "memory");
; #pragma unroll
;                 for (int j = 0; j < 4; ++j) v[j] += t[j];
;             }
;         }
.LBB0_641:
	v_lshl_add_u64 v[102:103], v[86:87], 0, s[6:7]
	global_load_dwordx4 v[106:109], v[102:103], off
	global_load_dwordx4 v[110:113], v[102:103], off offset:1024
	global_load_dwordx4 v[114:117], v[102:103], off offset:2048
	global_load_dwordx4 v[118:121], v[102:103], off offset:3072
	s_add_u32 s6, s6, 0x400000
	s_addc_u32 s7, s7, 0
	v_lshl_add_u64 v[102:103], v[86:87], 0, s[6:7]
	global_load_dwordx4 v[122:125], v[102:103], off
	global_load_dwordx4 v[126:129], v[102:103], off offset:1024
	global_load_dwordx4 v[130:133], v[102:103], off offset:2048
	global_load_dwordx4 v[134:137], v[102:103], off offset:3072
	s_add_u32 s6, s6, 0x400000
	s_addc_u32 s7, s7, 0
	v_lshl_add_u64 v[102:103], v[86:87], 0, s[6:7]
	global_load_dwordx4 v[138:141], v[102:103], off
	global_load_dwordx4 v[142:145], v[102:103], off offset:1024
	global_load_dwordx4 v[146:149], v[102:103], off offset:2048
	global_load_dwordx4 v[150:153], v[102:103], off offset:3072
	s_add_u32 s6, s6, 0x400000
	s_addc_u32 s7, s7, 0
	v_lshl_add_u64 v[102:103], v[86:87], 0, s[6:7]
	global_load_dwordx4 v[154:157], v[102:103], off
	global_load_dwordx4 v[158:161], v[102:103], off offset:1024
	global_load_dwordx4 v[162:165], v[102:103], off offset:2048
	global_load_dwordx4 v[166:169], v[102:103], off offset:3072
	s_add_u32 s6, s6, 0x400000
	s_addc_u32 s7, s7, 0
	v_lshl_add_u64 v[102:103], v[86:87], 0, s[6:7]
	global_load_dwordx4 v[170:173], v[102:103], off
	global_load_dwordx4 v[174:177], v[102:103], off offset:1024
	global_load_dwordx4 v[178:181], v[102:103], off offset:2048
	global_load_dwordx4 v[182:185], v[102:103], off offset:3072
	s_add_u32 s6, s6, 0x400000
	s_addc_u32 s7, s7, 0
	v_lshl_add_u64 v[102:103], v[86:87], 0, s[6:7]
	global_load_dwordx4 v[186:189], v[102:103], off
	global_load_dwordx4 v[190:193], v[102:103], off offset:1024
	global_load_dwordx4 v[194:197], v[102:103], off offset:2048
	global_load_dwordx4 v[198:201], v[102:103], off offset:3072
	s_add_u32 s6, s6, 0x400000
	s_addc_u32 s7, s7, 0
	s_waitcnt vmcnt(0)
; #define GAS __attribute__((address_space(1)))
; __device__ void phase_norm(const Params& p, int l, int which) {
;     ...
;         if (l == 1 && which == 0 && row >= NL) {
;             GAS const f32x4* pp = (GAS const f32x4*)(unsigned long long)((const float*)(p.ws + OFF_PART) + (size_t)(row - NL) * DM);
; #pragma unroll 1
;             for (int ks = 0; ks < SK_S; ++ks) {
;                 f32x4 t[4];
; #pragma unroll
;                 for (int j = 0; j < 4; ++j) t[j] = pp[(size_t)ks * (1024 * DM / 4) + lane + 64 * j];
;                 asm volatile("" ::: "memory");
; #pragma unroll
;                 for (int j = 0; j < 4; ++j) v[j] += t[j];
;             }
;         }
	v_pk_add_f32 v[62:63], v[62:63], v[108:109]
	v_pk_add_f32 v[60:61], v[60:61], v[106:107]
	v_pk_add_f32 v[38:39], v[38:39], v[112:113]
	v_pk_add_f32 v[36:37], v[36:37], v[110:111]
	v_pk_add_f32 v[30:31], v[30:31], v[116:117]
	v_pk_add_f32 v[28:29], v[28:29], v[114:115]
	v_pk_add_f32 v[14:15], v[14:15], v[120:121]
	v_pk_add_f32 v[12:13], v[12:13], v[118:119]
	v_pk_add_f32 v[62:63], v[62:63], v[124:125]
	v_pk_add_f32 v[60:61], v[60:61], v[122:123]
	v_pk_add_f32 v[38:39], v[38:39], v[128:129]
	v_pk_add_f32 v[36:37], v[36:37], v[126:127]
	v_pk_add_f32 v[30:31], v[30:31], v[132:133]
	v_pk_add_f32 v[28:29], v[28:29], v[130:131]
	v_pk_add_f32 v[14:15], v[14:15], v[136:137]
	v_pk_add_f32 v[12:13], v[12:13], v[134:135]
	v_pk_add_f32 v[62:63], v[62:63], v[140:141]
	v_pk_add_f32 v[60:61], v[60:61], v[138:139]
	v_pk_add_f32 v[38:39], v[38:39], v[144:145]
	v_pk_add_f32 v[36:37], v[36:37], v[142:143]
	v_pk_add_f32 v[30:31], v[30:31], v[148:149]
	v_pk_add_f32 v[28:29], v[28:29], v[146:147]
	v_pk_add_f32 v[14:15], v[14:15], v[152:153]
	v_pk_add_f32 v[12:13], v[12:13], v[150:151]
	v_pk_add_f32 v[62:63], v[62:63], v[156:157]
	v_pk_add_f32 v[60:61], v[60:61], v[154:155]
	v_pk_add_f32 v[38:39], v[38:39], v[160:161]
	v_pk_add_f32 v[36:37], v[36:37], v[158:159]
	v_pk_add_f32 v[30:31], v[30:31], v[164:165]
	v_pk_add_f32 v[28:29], v[28:29], v[162:163]
	v_pk_add_f32 v[14:15], v[14:15], v[168:169]
	v_pk_add_f32 v[12:13], v[12:13], v[166:167]
	v_pk_add_f32 v[62:63], v[62:63], v[172:173]
	v_pk_add_f32 v[60:61], v[60:61], v[170:171]
	v_pk_add_f32 v[38:39], v[38:39], v[176:177]
	v_pk_add_f32 v[36:37], v[36:37], v[174:175]
	v_pk_add_f32 v[30:31], v[30:31], v[180:181]
	v_pk_add_f32 v[28:29], v[28:29], v[178:179]
	v_pk_add_f32 v[14:15], v[14:15], v[184:185]
	v_pk_add_f32 v[12:13], v[12:13], v[182:183]
	v_pk_add_f32 v[62:63], v[62:63], v[188:189]
	v_pk_add_f32 v[60:61], v[60:61], v[186:187]
	v_pk_add_f32 v[38:39], v[38:39], v[192:193]
	v_pk_add_f32 v[36:37], v[36:37], v[190:191]
	v_pk_add_f32 v[30:31], v[30:31], v[196:197]
	v_pk_add_f32 v[28:29], v[28:29], v[194:195]
	v_pk_add_f32 v[14:15], v[14:15], v[200:201]
	v_pk_add_f32 v[12:13], v[12:13], v[198:199]
	v_lshl_add_u64 v[102:103], v[86:87], 0, s[6:7]
	global_load_dwordx4 v[106:109], v[102:103], off
	global_load_dwordx4 v[110:113], v[102:103], off offset:1024
	global_load_dwordx4 v[114:117], v[102:103], off offset:2048
	global_load_dwordx4 v[118:121], v[102:103], off offset:3072
	s_add_u32 s6, s6, 0x400000
	s_addc_u32 s7, s7, 0
	v_lshl_add_u64 v[102:103], v[86:87], 0, s[6:7]
	global_load_dwordx4 v[122:125], v[102:103], off
	global_load_dwordx4 v[126:129], v[102:103], off offset:1024
	global_load_dwordx4 v[130:133], v[102:103], off offset:2048
	global_load_dwordx4 v[134:137], v[102:103], off offset:3072
	s_add_u32 s6, s6, 0x400000
	s_addc_u32 s7, s7, 0
	v_lshl_add_u64 v[102:103], v[86:87], 0, s[6:7]
	global_load_dwordx4 v[138:141], v[102:103], off
	global_load_dwordx4 v[142:145], v[102:103], off offset:1024
	global_load_dwordx4 v[146:149], v[102:103], off offset:2048
	global_load_dwordx4 v[150:153], v[102:103], off offset:3072
	s_add_u32 s6, s6, 0x400000
	s_addc_u32 s7, s7, 0
	v_lshl_add_u64 v[102:103], v[86:87], 0, s[6:7]
	global_load_dwordx4 v[154:157], v[102:103], off
	global_load_dwordx4 v[158:161], v[102:103], off offset:1024
	global_load_dwordx4 v[162:165], v[102:103], off offset:2048
	global_load_dwordx4 v[166:169], v[102:103], off offset:3072
	s_add_u32 s6, s6, 0x400000
	s_addc_u32 s7, s7, 0
	v_lshl_add_u64 v[102:103], v[86:87], 0, s[6:7]
	global_load_dwordx4 v[170:173], v[102:103], off
	global_load_dwordx4 v[174:177], v[102:103], off offset:1024
	global_load_dwordx4 v[178:181], v[102:103], off offset:2048
	global_load_dwordx4 v[182:185], v[102:103], off offset:3072
	s_add_u32 s6, s6, 0x400000
	s_addc_u32 s7, s7, 0
	s_waitcnt vmcnt(0)
	v_pk_add_f32 v[62:63], v[62:63], v[108:109]
	v_pk_add_f32 v[60:61], v[60:61], v[106:107]
	v_pk_add_f32 v[38:39], v[38:39], v[112:113]
	v_pk_add_f32 v[36:37], v[36:37], v[110:111]
	v_pk_add_f32 v[30:31], v[30:31], v[116:117]
	v_pk_add_f32 v[28:29], v[28:29], v[114:115]
	v_pk_add_f32 v[14:15], v[14:15], v[120:121]
	v_pk_add_f32 v[12:13], v[12:13], v[118:119]
	v_pk_add_f32 v[62:63], v[62:63], v[124:125]
	v_pk_add_f32 v[60:61], v[60:61], v[122:123]
	v_pk_add_f32 v[38:39], v[38:39], v[128:129]
	v_pk_add_f32 v[36:37], v[36:37], v[126:127]
	v_pk_add_f32 v[30:31], v[30:31], v[132:133]
	v_pk_add_f32 v[28:29], v[28:29], v[130:131]
	v_pk_add_f32 v[14:15], v[14:15], v[136:137]
	v_pk_add_f32 v[12:13], v[12:13], v[134:135]
	v_pk_add_f32 v[62:63], v[62:63], v[140:141]
	v_pk_add_f32 v[60:61], v[60:61], v[138:139]
	v_pk_add_f32 v[38:39], v[38:39], v[144:145]
	v_pk_add_f32 v[36:37], v[36:37], v[142:143]
	v_pk_add_f32 v[30:31], v[30:31], v[148:149]
	v_pk_add_f32 v[28:29], v[28:29], v[146:147]
	v_pk_add_f32 v[14:15], v[14:15], v[152:153]
	v_pk_add_f32 v[12:13], v[12:13], v[150:151]
	v_pk_add_f32 v[62:63], v[62:63], v[156:157]
	v_pk_add_f32 v[60:61], v[60:61], v[154:155]
	v_pk_add_f32 v[38:39], v[38:39], v[160:161]
	v_pk_add_f32 v[36:37], v[36:37], v[158:159]
	v_pk_add_f32 v[30:31], v[30:31], v[164:165]
	v_pk_add_f32 v[28:29], v[28:29], v[162:163]
	v_pk_add_f32 v[14:15], v[14:15], v[168:169]
	v_pk_add_f32 v[12:13], v[12:13], v[166:167]
	v_pk_add_f32 v[62:63], v[62:63], v[172:173]
	v_pk_add_f32 v[60:61], v[60:61], v[170:171]
	v_pk_add_f32 v[38:39], v[38:39], v[176:177]
	v_pk_add_f32 v[36:37], v[36:37], v[174:175]
	v_pk_add_f32 v[30:31], v[30:31], v[180:181]
	v_pk_add_f32 v[28:29], v[28:29], v[178:179]
	v_pk_add_f32 v[14:15], v[14:15], v[184:185]
	v_pk_add_f32 v[12:13], v[12:13], v[182:183]
	s_branch .LBB0_634
